# v033_fence5
# speedup vs baseline: 1.0274x; 1.0274x over previous
; template <bool SB>
; DEVI void attn_item(const Params& p, char* lds, int r0, int nq, int qpos0, long kvb, int head, int jbeg, int jend, int pmode, int pidx, unsigned fval) {
;     ...
;   if (!SB && pmode == 2) {
;     if (tid == 0) {
;       unsigned* f = (unsigned*)(p.ws + W_BAR) + 3456 + pidx;
;       unsigned sp_ = 0;
;       while (__hip_atomic_load(f, __ATOMIC_RELAXED, __HIP_MEMORY_SCOPE_AGENT) != fval) { __builtin_amdgcn_s_sleep(2); if (++sp_ > (1u << 24)) break; }
;     }
;     __syncthreads();
;     __threadfence();
;     const float* po = (const float*)(p.ws + W_PART) + ((long)(pidx * 4 + w) * 66) * 64 + lane;
;     const float mb = po[64 * 64], lb = po[65 * 64];
;     const float mn = fmaxf(m_run, mb);
;     const float sa = __builtin_amdgcn_exp2f(m_run - mn), sb2 = __builtin_amdgcn_exp2f(mb - mn);
;     l_run = l_run * sa + lb * sb2;
; #pragma unroll
;     for (int b = 0; b < 4; ++b)
; #pragma unroll
;       for (int r = 0; r < 16; ++r) o[b][r] = o[b][r] * sa + po[(b * 16 + r) * 64] * sb2;
;   }
.LBB0_815:
	s_or_b64 exec, exec, s[8:9]
	v_readlane_b32 s8, v240, 41
	v_readlane_b32 s9, v240, 42
	v_lshl_add_u32 v0, s90, 2, v202
	s_waitcnt vmcnt(0) lgkmcnt(0)
	v_mov_b64_e32 v[2:3], s[8:9]
	s_movk_i32 s8, 0x4200
	v_mad_i64_i32 v[2:3], s[8:9], v0, s8, v[2:3]
	v_lshlrev_b32_e32 v0, 2, v6
	v_lshl_add_u64 v[4:5], v[2:3], 0, v[0:1]
	v_add_co_u32_e32 v2, vcc, 0x4000, v4
	s_barrier
	s_nop 0
	v_addc_co_u32_e32 v3, vcc, 0, v5, vcc
	buffer_inv sc1
	global_load_dword v0, v[2:3], off
	global_load_dword v177, v[2:3], off offset:256
	global_load_dword v8, v[4:5], off
	global_load_dword v9, v[4:5], off offset:256
	global_load_dword v10, v[4:5], off offset:512
	global_load_dword v11, v[4:5], off offset:768
	global_load_dword v12, v[4:5], off offset:1024
	global_load_dword v13, v[4:5], off offset:1280
	global_load_dword v14, v[4:5], off offset:1536
	global_load_dword v15, v[4:5], off offset:1792
	global_load_dword v80, v[4:5], off offset:2048
	global_load_dword v81, v[4:5], off offset:2304
	v_max_f32_e32 v3, v204, v204
	s_movk_i32 s8, 0x1000
	s_waitcnt vmcnt(11)
	v_max_f32_e32 v2, v0, v0
	v_max_f32_e32 v3, v3, v2
	v_sub_f32_e32 v0, v0, v3
	v_exp_f32_e32 v0, v0
	v_sub_f32_e32 v2, v204, v3
	v_exp_f32_e32 v2, v2
	s_waitcnt vmcnt(0)
	v_pk_mul_f32 v[88:89], v[0:1], v[80:81] op_sel_hi:[0,1]
	global_load_dword v80, v[4:5], off offset:2560
	global_load_dword v81, v[4:5], off offset:2816
	v_pk_mul_f32 v[8:9], v[8:9], v[0:1] op_sel_hi:[1,0]
	v_pk_mul_f32 v[10:11], v[0:1], v[10:11] op_sel_hi:[0,1]
	v_pk_mul_f32 v[12:13], v[0:1], v[12:13] op_sel_hi:[0,1]
	v_pk_mul_f32 v[14:15], v[0:1], v[14:15] op_sel_hi:[0,1]
	v_mul_f32_e32 v94, v78, v2
	v_mul_f32_e32 v106, v62, v2
	v_mul_f32_e32 v110, v46, v2
	v_mul_f32_e32 v142, v30, v2
	s_waitcnt vmcnt(0)
	v_pk_mul_f32 v[90:91], v[0:1], v[80:81] op_sel_hi:[0,1]
	global_load_dword v80, v[4:5], off offset:3072
	global_load_dword v81, v[4:5], off offset:3328
	global_load_dword v3, v[4:5], off offset:3584
	s_waitcnt vmcnt(1)
	v_pk_mul_f32 v[92:93], v[0:1], v[80:81] op_sel_hi:[0,1]
	s_waitcnt vmcnt(0)
	v_mul_f32_e32 v96, v0, v3
	global_load_dword v3, v[4:5], off offset:3840
	v_mov_b32_e32 v80, v79
	v_mov_b32_e32 v81, v0
	s_waitcnt vmcnt(0)
	v_pk_mul_f32 v[80:81], v[80:81], v[2:3]
	s_nop 0
	v_mov_b32_e32 v95, v80
	v_mov_b32_e32 v97, v81
	v_pk_fma_f32 v[80:81], v[64:65], v[2:3], v[8:9] op_sel_hi:[1,0,1]
	v_add_co_u32_e32 v8, vcc, s8, v4
	s_movk_i32 s8, 0x2000
	s_nop 0
	v_addc_co_u32_e32 v9, vcc, 0, v5, vcc
	v_pk_fma_f32 v[82:83], v[66:67], v[2:3], v[10:11] op_sel_hi:[1,0,1]
	v_add_co_u32_e32 v10, vcc, s8, v4
	v_pk_fma_f32 v[84:85], v[68:69], v[2:3], v[12:13] op_sel_hi:[1,0,1]
	s_nop 0
	v_addc_co_u32_e32 v11, vcc, 0, v5, vcc
	v_pk_fma_f32 v[86:87], v[70:71], v[2:3], v[14:15] op_sel_hi:[1,0,1]
	v_pk_fma_f32 v[88:89], v[72:73], v[2:3], v[88:89] op_sel_hi:[1,0,1]
	v_pk_fma_f32 v[90:91], v[74:75], v[2:3], v[90:91] op_sel_hi:[1,0,1]
	v_pk_fma_f32 v[92:93], v[76:77], v[2:3], v[92:93] op_sel_hi:[1,0,1]
	v_pk_add_f32 v[94:95], v[94:95], v[96:97]
	global_load_dword v12, v[10:11], off offset:-4096
	global_load_dword v13, v[8:9], off offset:256
	global_load_dword v14, v[8:9], off offset:512
	global_load_dword v15, v[8:9], off offset:768
	global_load_dword v96, v[8:9], off offset:1024
	global_load_dword v97, v[8:9], off offset:1280
	global_load_dword v98, v[8:9], off offset:1536
	global_load_dword v99, v[8:9], off offset:1792
	global_load_dword v100, v[8:9], off offset:2048
	global_load_dword v101, v[8:9], off offset:2304
	global_load_dword v102, v[8:9], off offset:2560
	global_load_dword v103, v[8:9], off offset:2816
	global_load_dword v104, v[8:9], off offset:3072
	global_load_dword v105, v[8:9], off offset:3328
	global_load_dword v3, v[8:9], off offset:3584
	s_movk_i32 s8, 0x3000
	v_add_co_u32_e32 v4, vcc, s8, v4
	s_waitcnt vmcnt(13)
	v_pk_mul_f32 v[12:13], v[0:1], v[12:13] op_sel_hi:[0,1]
	s_waitcnt vmcnt(11)
	v_pk_mul_f32 v[14:15], v[0:1], v[14:15] op_sel_hi:[0,1]
	s_waitcnt vmcnt(9)
	v_pk_mul_f32 v[96:97], v[0:1], v[96:97] op_sel_hi:[0,1]
	s_waitcnt vmcnt(7)
	v_pk_mul_f32 v[98:99], v[0:1], v[98:99] op_sel_hi:[0,1]
	s_waitcnt vmcnt(5)
	v_pk_mul_f32 v[100:101], v[0:1], v[100:101] op_sel_hi:[0,1]
	s_waitcnt vmcnt(3)
	v_pk_mul_f32 v[102:103], v[0:1], v[102:103] op_sel_hi:[0,1]
	s_waitcnt vmcnt(1)
	v_pk_mul_f32 v[104:105], v[0:1], v[104:105] op_sel_hi:[0,1]
	s_waitcnt vmcnt(0)
	v_mul_f32_e32 v108, v0, v3
	global_load_dword v3, v[8:9], off offset:3840
	v_mov_b32_e32 v8, v63
	v_mov_b32_e32 v9, v0
	v_addc_co_u32_e32 v5, vcc, 0, v5, vcc
	s_waitcnt vmcnt(0)
; template <bool SB>
; DEVI void attn_item(const Params& p, char* lds, int r0, int nq, int qpos0, long kvb, int head, int jbeg, int jend, int pmode, int pidx, unsigned fval) {
;     ...
;     const float* po = (const float*)(p.ws + W_PART) + ((long)(pidx * 4 + w) * 66) * 64 + lane;
;     const float mb = po[64 * 64], lb = po[65 * 64];
;     const float mn = fmaxf(m_run, mb);
;     const float sa = __builtin_amdgcn_exp2f(m_run - mn), sb2 = __builtin_amdgcn_exp2f(mb - mn);
;     l_run = l_run * sa + lb * sb2;
; #pragma unroll
;     for (int b = 0; b < 4; ++b)
; #pragma unroll
;       for (int r = 0; r < 16; ++r) o[b][r] = o[b][r] * sa + po[(b * 16 + r) * 64] * sb2;
;   }
	v_pk_mul_f32 v[8:9], v[8:9], v[2:3]
	s_nop 0
	v_mov_b32_e32 v107, v8
	v_mov_b32_e32 v109, v9
	v_pk_fma_f32 v[112:113], v[48:49], v[2:3], v[12:13] op_sel_hi:[1,0,1]
	v_pk_fma_f32 v[114:115], v[50:51], v[2:3], v[14:15] op_sel_hi:[1,0,1]
	v_pk_fma_f32 v[116:117], v[52:53], v[2:3], v[96:97] op_sel_hi:[1,0,1]
	global_load_dword v8, v[10:11], off
	global_load_dword v9, v[10:11], off offset:256
	global_load_dword v12, v[10:11], off offset:512
	global_load_dword v13, v[10:11], off offset:768
	global_load_dword v14, v[10:11], off offset:1024
	global_load_dword v15, v[10:11], off offset:1280
	global_load_dword v96, v[10:11], off offset:1536
	global_load_dword v97, v[10:11], off offset:1792
	v_pk_fma_f32 v[122:123], v[58:59], v[2:3], v[102:103] op_sel_hi:[1,0,1]
	v_pk_fma_f32 v[124:125], v[60:61], v[2:3], v[104:105] op_sel_hi:[1,0,1]
	v_pk_fma_f32 v[118:119], v[54:55], v[2:3], v[98:99] op_sel_hi:[1,0,1]
	v_pk_fma_f32 v[120:121], v[56:57], v[2:3], v[100:101] op_sel_hi:[1,0,1]
	v_pk_add_f32 v[126:127], v[106:107], v[108:109]
	s_waitcnt vmcnt(6)
	v_pk_mul_f32 v[8:9], v[0:1], v[8:9] op_sel_hi:[0,1]
	s_waitcnt vmcnt(4)
	v_pk_mul_f32 v[12:13], v[0:1], v[12:13] op_sel_hi:[0,1]
	s_waitcnt vmcnt(2)
	v_pk_mul_f32 v[14:15], v[0:1], v[14:15] op_sel_hi:[0,1]
	s_waitcnt vmcnt(0)
	v_pk_mul_f32 v[102:103], v[0:1], v[96:97] op_sel_hi:[0,1]
	global_load_dword v96, v[10:11], off offset:2048
	global_load_dword v97, v[10:11], off offset:2304
	s_waitcnt vmcnt(0)
	v_pk_mul_f32 v[104:105], v[0:1], v[96:97] op_sel_hi:[0,1]
	global_load_dword v96, v[10:11], off offset:2560
	global_load_dword v97, v[10:11], off offset:2816
	s_waitcnt vmcnt(0)
	v_pk_mul_f32 v[106:107], v[0:1], v[96:97] op_sel_hi:[0,1]
	global_load_dword v96, v[10:11], off offset:3072
	global_load_dword v97, v[10:11], off offset:3328
	global_load_dword v3, v[10:11], off offset:3584
	s_waitcnt vmcnt(1)
	v_pk_mul_f32 v[108:109], v[0:1], v[96:97] op_sel_hi:[0,1]
	s_waitcnt vmcnt(0)
	v_mul_f32_e32 v128, v0, v3
	global_load_dword v3, v[10:11], off offset:3840
	v_mov_b32_e32 v10, v47
	v_mov_b32_e32 v11, v0
	s_waitcnt vmcnt(0)
	v_pk_mul_f32 v[10:11], v[10:11], v[2:3]
	s_nop 0
	v_mov_b32_e32 v111, v10
	v_mov_b32_e32 v129, v11
	v_pk_fma_f32 v[96:97], v[32:33], v[2:3], v[8:9] op_sel_hi:[1,0,1]
	v_pk_fma_f32 v[98:99], v[34:35], v[2:3], v[12:13] op_sel_hi:[1,0,1]
	v_pk_fma_f32 v[100:101], v[36:37], v[2:3], v[14:15] op_sel_hi:[1,0,1]
	v_pk_add_f32 v[110:111], v[110:111], v[128:129]
	global_load_dword v8, v[4:5], off
	global_load_dword v9, v[4:5], off offset:256
	global_load_dword v10, v[4:5], off offset:512
	global_load_dword v11, v[4:5], off offset:768
	global_load_dword v12, v[4:5], off offset:1024
	global_load_dword v13, v[4:5], off offset:1280
	global_load_dword v14, v[4:5], off offset:1536
	global_load_dword v15, v[4:5], off offset:1792
	global_load_dword v128, v[4:5], off offset:2048
	global_load_dword v129, v[4:5], off offset:2304
	v_pk_fma_f32 v[102:103], v[38:39], v[2:3], v[102:103] op_sel_hi:[1,0,1]
	v_pk_fma_f32 v[104:105], v[40:41], v[2:3], v[104:105] op_sel_hi:[1,0,1]
	v_pk_fma_f32 v[106:107], v[42:43], v[2:3], v[106:107] op_sel_hi:[1,0,1]
	v_pk_fma_f32 v[108:109], v[44:45], v[2:3], v[108:109] op_sel_hi:[1,0,1]
	s_waitcnt vmcnt(8)
	v_pk_mul_f32 v[8:9], v[0:1], v[8:9] op_sel_hi:[0,1]
	s_waitcnt vmcnt(6)
	v_pk_mul_f32 v[10:11], v[0:1], v[10:11] op_sel_hi:[0,1]
	s_waitcnt vmcnt(4)
	v_pk_mul_f32 v[12:13], v[0:1], v[12:13] op_sel_hi:[0,1]
	s_waitcnt vmcnt(2)
	v_pk_mul_f32 v[14:15], v[0:1], v[14:15] op_sel_hi:[0,1]
	s_waitcnt vmcnt(0)
	v_pk_mul_f32 v[136:137], v[0:1], v[128:129] op_sel_hi:[0,1]
	global_load_dword v128, v[4:5], off offset:2560
	global_load_dword v129, v[4:5], off offset:2816
	s_waitcnt vmcnt(0)
	v_pk_mul_f32 v[138:139], v[0:1], v[128:129] op_sel_hi:[0,1]
	global_load_dword v128, v[4:5], off offset:3072
	global_load_dword v129, v[4:5], off offset:3328
	global_load_dword v3, v[4:5], off offset:3584
	s_waitcnt vmcnt(1)
	v_pk_mul_f32 v[140:141], v[0:1], v[128:129] op_sel_hi:[0,1]
	s_waitcnt vmcnt(0)
	v_mul_f32_e32 v178, v0, v3
	global_load_dword v3, v[4:5], off offset:3840
	v_mov_b32_e32 v4, v31
	v_mov_b32_e32 v5, v0
	s_waitcnt vmcnt(0)
	v_pk_mul_f32 v[4:5], v[4:5], v[2:3]
	v_pk_fma_f32 v[128:129], v[16:17], v[2:3], v[8:9] op_sel_hi:[1,0,1]
	v_pk_fma_f32 v[130:131], v[18:19], v[2:3], v[10:11] op_sel_hi:[1,0,1]
	v_pk_fma_f32 v[132:133], v[20:21], v[2:3], v[12:13] op_sel_hi:[1,0,1]
	v_pk_fma_f32 v[134:135], v[22:23], v[2:3], v[14:15] op_sel_hi:[1,0,1]
	v_pk_fma_f32 v[136:137], v[24:25], v[2:3], v[136:137] op_sel_hi:[1,0,1]
	v_pk_fma_f32 v[138:139], v[26:27], v[2:3], v[138:139] op_sel_hi:[1,0,1]
	v_pk_fma_f32 v[140:141], v[28:29], v[2:3], v[140:141] op_sel_hi:[1,0,1]
	v_mov_b32_e32 v3, v0
	v_mov_b32_e32 v143, v4
	v_mov_b32_e32 v179, v5
	v_pk_mul_f32 v[2:3], v[176:177], v[2:3]
	v_pk_add_f32 v[142:143], v[142:143], v[178:179]
	v_add_f32_e32 v0, v2, v3

; template <bool SB>
; DEVI void attn_item(const Params& p, char* lds, int r0, int nq, int qpos0, long kvb, int head, int jbeg, int jend, int pmode, int pidx, unsigned fval) {
;     ...
;   if (!SB && pmode == 1) {
;     float* po = (float*)(p.ws + W_PART) + ((long)(pidx * 4 + w) * 66) * 64 + lane;
; #pragma unroll
;     for (int b = 0; b < 4; ++b)
; #pragma unroll
;       for (int r = 0; r < 16; ++r) po[(b * 16 + r) * 64] = o[b][r];
;     po[64 * 64] = m_run; po[65 * 64] = l_run;
;     __threadfence();
;     __syncthreads();
;     if (tid == 0) __hip_atomic_store((unsigned*)(p.ws + W_BAR) + 3456 + pidx, fval, __ATOMIC_RELAXED, __HIP_MEMORY_SCOPE_AGENT);
;     return;
.LBB0_822:
	v_readlane_b32 s0, v240, 41
	v_readlane_b32 s1, v240, 42
	v_lshl_add_u32 v0, s90, 2, v202
	s_waitcnt lgkmcnt(0)
	v_mov_b64_e32 v[2:3], s[0:1]
	s_movk_i32 s0, 0x4200
	v_mad_i64_i32 v[2:3], s[0:1], v0, s0, v[2:3]
	v_lshlrev_b32_e32 v0, 2, v6
	v_lshl_add_u64 v[2:3], v[2:3], 0, v[0:1]
	s_movk_i32 s0, 0x1000
	v_add_co_u32_e32 v4, vcc, s0, v2
	s_movk_i32 s0, 0x2000
	s_nop 0
	v_addc_co_u32_e32 v5, vcc, 0, v3, vcc
	v_add_co_u32_e32 v6, vcc, s0, v2
	s_movk_i32 s0, 0x3000
	s_nop 0
	v_addc_co_u32_e32 v7, vcc, 0, v3, vcc
	global_store_dword v[2:3], v64, off
	global_store_dword v[2:3], v65, off offset:256
	global_store_dword v[2:3], v66, off offset:512
	global_store_dword v[2:3], v67, off offset:768
	global_store_dword v[2:3], v68, off offset:1024
	global_store_dword v[2:3], v69, off offset:1280
	global_store_dword v[2:3], v70, off offset:1536
	global_store_dword v[2:3], v71, off offset:1792
	global_store_dword v[2:3], v72, off offset:2048
	global_store_dword v[2:3], v73, off offset:2304
	global_store_dword v[2:3], v74, off offset:2560
	global_store_dword v[2:3], v75, off offset:2816
	global_store_dword v[2:3], v76, off offset:3072
	global_store_dword v[2:3], v77, off offset:3328
	global_store_dword v[2:3], v78, off offset:3584
	global_store_dword v[2:3], v79, off offset:3840
	global_store_dword v[6:7], v48, off offset:-4096
	global_store_dword v[4:5], v49, off offset:256
	global_store_dword v[4:5], v50, off offset:512
	global_store_dword v[4:5], v51, off offset:768
	global_store_dword v[4:5], v52, off offset:1024
	global_store_dword v[4:5], v53, off offset:1280
	global_store_dword v[4:5], v54, off offset:1536
	global_store_dword v[4:5], v55, off offset:1792
	global_store_dword v[4:5], v56, off offset:2048
	global_store_dword v[4:5], v57, off offset:2304
	global_store_dword v[4:5], v58, off offset:2560
	global_store_dword v[4:5], v59, off offset:2816
	global_store_dword v[4:5], v60, off offset:3072
	global_store_dword v[4:5], v61, off offset:3328
	global_store_dword v[4:5], v62, off offset:3584
	global_store_dword v[4:5], v63, off offset:3840
	global_store_dword v[6:7], v32, off
	global_store_dword v[6:7], v33, off offset:256
	global_store_dword v[6:7], v34, off offset:512
	global_store_dword v[6:7], v35, off offset:768
	global_store_dword v[6:7], v36, off offset:1024
	global_store_dword v[6:7], v37, off offset:1280
	global_store_dword v[6:7], v38, off offset:1536
	global_store_dword v[6:7], v39, off offset:1792
	global_store_dword v[6:7], v40, off offset:2048
	global_store_dword v[6:7], v41, off offset:2304
	global_store_dword v[6:7], v42, off offset:2560
	global_store_dword v[6:7], v43, off offset:2816
	global_store_dword v[6:7], v44, off offset:3072
	global_store_dword v[6:7], v45, off offset:3328
	global_store_dword v[6:7], v46, off offset:3584
	global_store_dword v[6:7], v47, off offset:3840
	v_add_co_u32_e32 v4, vcc, s0, v2
	s_nop 1
	v_addc_co_u32_e32 v5, vcc, 0, v3, vcc
	v_add_co_u32_e32 v2, vcc, 0x4000, v2
	global_store_dword v[4:5], v16, off
	global_store_dword v[4:5], v17, off offset:256
	global_store_dword v[4:5], v18, off offset:512
	global_store_dword v[4:5], v19, off offset:768
	global_store_dword v[4:5], v20, off offset:1024
	global_store_dword v[4:5], v21, off offset:1280
	global_store_dword v[4:5], v22, off offset:1536
	global_store_dword v[4:5], v23, off offset:1792
	global_store_dword v[4:5], v24, off offset:2048
	global_store_dword v[4:5], v25, off offset:2304
	global_store_dword v[4:5], v26, off offset:2560
	global_store_dword v[4:5], v27, off offset:2816
	global_store_dword v[4:5], v28, off offset:3072
	global_store_dword v[4:5], v29, off offset:3328
	global_store_dword v[4:5], v30, off offset:3584
	global_store_dword v[4:5], v31, off offset:3840
	v_addc_co_u32_e32 v3, vcc, 0, v3, vcc
	v_cmp_eq_u32_e32 vcc, 0, v201
	global_store_dword v[2:3], v204, off
	global_store_dword v[2:3], v176, off offset:256
	s_waitcnt vmcnt(0)
	s_barrier
	s_and_saveexec_b64 s[0:1], vcc
	s_cbranch_execz .LBB0_824
	buffer_wbl2 sc1
	s_waitcnt vmcnt(0)
	s_mov_b32 s91, s89
	s_lshl_b64 s[4:5], s[90:91], 2
	v_readlane_b32 s6, v240, 39
	s_add_u32 s4, s6, s4
	v_readlane_b32 s6, v240, 40
	s_addc_u32 s5, s6, s5
	global_store_dword v1, v222, s[4:5] sc1
